# mla_up Q epilogue: row-group rms statistics prefetched one group early
# baseline (speedup 1.0000x reference)
; DI u32x2 pk4(float a, float b, float c, float d) { u32x2 r; r.x = pk2(a, b); r.y = pk2(c, d); return r; }
;     ...
;             for (int mi = 0; mi < MI; ++mi) {
;                 const int tok = tok0 + wr * C::WROWS + mi * 32 + li, tl = tok - half * HALF_T;
;                 const f32x4 s0 = *(const f32x4*)(SSQ + tok * 12), s1 = *(const f32x4*)(SSQ + tok * 12 + 4);
;                 const float rs = __builtin_amdgcn_rsqf(((s0.x + s0.y) + (s0.z + s0.w) + (s1.x + s1.y) + (s1.z + s1.w)) * (1.f / 512.f) + EPS) * QSCALE;
;                 bf16_t* dst = Q + (size_t)tl * 3072 + head * 192 + part * 64;
;                 bf16_t* drow0 = Q + (size_t)(tok0 - half * HALF_T + wr * C::WROWS + mi * 32) * 3072 + head * 192 + part * 64;
;                 if (part < 2) {
;                     wave_rows_store(ebuf, l, drow0, 3072, [&](int ni, int g) { return pk4(acc[mi][ni][4 * g] * rs, acc[mi][ni][4 * g + 1] * rs, acc[mi][ni][4 * g + 2] * rs, acc[mi][ni][4 * g + 3] * rs); });
;                 } else {
; #pragma unroll
;                     for (int g = 0; g < 4; ++g) {
;                         const int i0 = 8 * g + 4 * h;
;                         const f32x4 c4 = *(const f32x4*)(COS + tok * 32 + i0), s4 = *(const f32x4*)(SIN + tok * 32 + i0);
;                         float o1[4], o2[4];
; #pragma unroll
;                         for (int c = 0; c < 4; ++c) { const float x1 = acc[mi][0][4 * g + c] * rs, x2 = acc[mi][1][4 * g + c] * rs; o1[c] = x1 * c4[c] - x2 * s4[c]; o2[c] = x1 * s4[c] + x2 * c4[c]; }
;                         *(u32x2*)(dst + i0) = pk4(o1[0], o1[1], o1[2], o1[3]);
;                         *(u32x2*)(dst + 32 + i0) = pk4(o2[0], o2[1], o2[2], o2[3]);
;                     }
.LBB0_824:
	s_or_b64 exec, exec, s[4:5]
	v_add_u32_e32 v96, 0x180, v136
	v_ashrrev_i32_e32 v97, 31, v96
	v_lshl_add_u64 v[102:103], v[96:97], 2, s[10:11]
	global_load_dwordx4 v[98:101], v[102:103], off
	global_load_dwordx4 v[120:123], v[102:103], off offset:1536
	global_load_dwordx4 v[124:127], v[102:103], off offset:1552
	s_nop 0
	global_load_dwordx4 v[102:105], v[102:103], off offset:16
	s_waitcnt vmcnt(1)
	v_add_f32_e32 v97, v98, v99
	v_add_f32_e32 v98, v100, v101
	s_waitcnt vmcnt(0)
	v_add_f32_e32 v99, v102, v103
	v_add_f32_e32 v97, v97, v98
	v_add_f32_e32 v97, v97, v99
	v_add_f32_e32 v98, v104, v105
	v_add_f32_e32 v97, v98, v97
	v_fmamk_f32 v97, v97, 0x3b000000, v252
	v_rsq_f32_e32 v97, v97
	s_nop 0
	v_mul_f32_e32 v98, 0x3dd53b94, v97
	s_and_saveexec_b64 s[4:5], s[38:39]
	s_xor_b64 s[4:5], exec, s[4:5]
	s_cbranch_execz .LBB0_826
	v_or_b32_e32 v97, 32, v139
	v_subrev_u32_e32 v99, s46, v97
	v_mad_i64_i32 v[112:113], s[18:19], v99, s7, v[128:129]
	v_lshlrev_b32_e32 v100, 5, v97
	v_ashrrev_i32_e32 v101, 31, v100
	v_readlane_b32 s18, v254, 34
	v_lshlrev_b64 v[100:101], 2, v[100:101]
	v_readlane_b32 s19, v254, 35
	v_mov_b32_e32 v131, v177
	v_pk_mul_f32 v[116:117], v[64:65], v[98:99] op_sel_hi:[1,0]
	v_lshl_add_u64 v[102:103], s[18:19], 0, v[100:101]
	v_readlane_b32 s18, v254, 36
	v_readlane_b32 s19, v254, 37
	v_pk_mul_f32 v[114:115], v[80:81], v[98:99] op_sel_hi:[1,0]
	v_mov_b32_e32 v133, v177
	v_lshl_add_u64 v[108:109], s[18:19], 0, v[100:101]
	v_lshl_add_u64 v[100:101], v[102:103], 0, v[130:131]
	v_lshl_add_u64 v[102:103], v[108:109], 0, v[130:131]
	global_load_dwordx4 v[104:107], v[100:101], off
	global_load_dwordx4 v[108:111], v[102:103], off
	s_waitcnt vmcnt(0)
	v_pk_mul_f32 v[118:119], v[116:117], v[108:109]
	s_nop 0
	v_pk_fma_f32 v[118:119], v[114:115], v[104:105], v[118:119] neg_lo:[0,0,1] neg_hi:[0,0,1]
	v_pk_mul_f32 v[108:109], v[114:115], v[108:109]
	v_pk_mul_f32 v[114:115], v[66:67], v[98:99] op_sel_hi:[1,0]
	v_pk_fma_f32 v[108:109], v[116:117], v[104:105], v[108:109]
	v_pk_mul_f32 v[104:105], v[82:83], v[98:99] op_sel_hi:[1,0]
	v_pk_mul_f32 v[116:117], v[114:115], v[110:111]
	v_cvt_pk_bf16_f32 v108, v108, v109
	v_pk_fma_f32 v[116:117], v[104:105], v[106:107], v[116:117] neg_lo:[0,0,1] neg_hi:[0,0,1]
	v_pk_mul_f32 v[104:105], v[104:105], v[110:111]
	v_cvt_pk_bf16_f32 v110, v118, v119
	v_pk_fma_f32 v[106:107], v[114:115], v[106:107], v[104:105]
	v_cvt_pk_bf16_f32 v111, v116, v117
	v_lshl_add_u64 v[104:105], v[112:113], 0, v[132:133]
	v_cvt_pk_bf16_f32 v109, v106, v107
	global_store_dwordx2 v[104:105], v[110:111], off
	global_store_dwordx2 v[104:105], v[108:109], off offset:64
	global_load_dwordx4 v[106:109], v[100:101], off offset:32
	s_nop 0
	global_load_dwordx4 v[110:113], v[102:103], off offset:32
	v_pk_mul_f32 v[116:117], v[68:69], v[98:99] op_sel_hi:[1,0]
	v_pk_mul_f32 v[114:115], v[84:85], v[98:99] op_sel_hi:[1,0]
	s_waitcnt vmcnt(0)
	v_pk_mul_f32 v[118:119], v[116:117], v[110:111]
	s_nop 0
	v_pk_fma_f32 v[118:119], v[114:115], v[106:107], v[118:119] neg_lo:[0,0,1] neg_hi:[0,0,1]
	v_pk_mul_f32 v[110:111], v[114:115], v[110:111]
	v_pk_mul_f32 v[114:115], v[70:71], v[98:99] op_sel_hi:[1,0]
	v_pk_fma_f32 v[106:107], v[116:117], v[106:107], v[110:111]
	v_pk_mul_f32 v[110:111], v[86:87], v[98:99] op_sel_hi:[1,0]
	v_pk_mul_f32 v[116:117], v[114:115], v[112:113]
	v_cvt_pk_bf16_f32 v106, v106, v107
	v_pk_fma_f32 v[116:117], v[110:111], v[108:109], v[116:117] neg_lo:[0,0,1] neg_hi:[0,0,1]
	v_pk_mul_f32 v[110:111], v[110:111], v[112:113]
	s_nop 0
	v_pk_fma_f32 v[108:109], v[114:115], v[108:109], v[110:111]
	v_cvt_pk_bf16_f32 v110, v118, v119
	v_cvt_pk_bf16_f32 v111, v116, v117
	v_cvt_pk_bf16_f32 v107, v108, v109
	global_store_dwordx2 v[104:105], v[110:111], off offset:16
	global_store_dwordx2 v[104:105], v[106:107], off offset:80
	global_load_dwordx4 v[106:109], v[100:101], off offset:64
	s_nop 0
	global_load_dwordx4 v[110:113], v[102:103], off offset:64
	v_pk_mul_f32 v[116:117], v[72:73], v[98:99] op_sel_hi:[1,0]
	v_pk_mul_f32 v[114:115], v[88:89], v[98:99] op_sel_hi:[1,0]
	s_waitcnt vmcnt(0)
	v_pk_mul_f32 v[118:119], v[116:117], v[110:111]
	s_nop 0
	v_pk_fma_f32 v[118:119], v[114:115], v[106:107], v[118:119] neg_lo:[0,0,1] neg_hi:[0,0,1]
	v_pk_mul_f32 v[110:111], v[114:115], v[110:111]
	v_pk_mul_f32 v[114:115], v[74:75], v[98:99] op_sel_hi:[1,0]
	v_pk_fma_f32 v[106:107], v[116:117], v[106:107], v[110:111]
	v_pk_mul_f32 v[110:111], v[90:91], v[98:99] op_sel_hi:[1,0]
	v_pk_mul_f32 v[116:117], v[114:115], v[112:113]
	v_cvt_pk_bf16_f32 v106, v106, v107
	v_pk_fma_f32 v[116:117], v[110:111], v[108:109], v[116:117] neg_lo:[0,0,1] neg_hi:[0,0,1]
	v_pk_mul_f32 v[110:111], v[110:111], v[112:113]
	v_pk_mul_f32 v[112:113], v[76:77], v[98:99] op_sel_hi:[1,0]
	v_pk_fma_f32 v[108:109], v[114:115], v[108:109], v[110:111]
	v_cvt_pk_bf16_f32 v110, v118, v119
	v_cvt_pk_bf16_f32 v111, v116, v117
	v_cvt_pk_bf16_f32 v107, v108, v109
	global_store_dwordx2 v[104:105], v[110:111], off offset:32
	global_store_dwordx2 v[104:105], v[106:107], off offset:96
	global_load_dwordx4 v[106:109], v[100:101], off offset:96
	s_nop 0
	global_load_dwordx4 v[100:103], v[102:103], off offset:96
	v_pk_mul_f32 v[110:111], v[92:93], v[98:99] op_sel_hi:[1,0]
	s_waitcnt vmcnt(0)
	v_pk_mul_f32 v[114:115], v[112:113], v[100:101]
	v_pk_mul_f32 v[100:101], v[110:111], v[100:101]
	v_pk_fma_f32 v[114:115], v[110:111], v[106:107], v[114:115] neg_lo:[0,0,1] neg_hi:[0,0,1]
	v_pk_fma_f32 v[100:101], v[112:113], v[106:107], v[100:101]
	v_pk_mul_f32 v[106:107], v[94:95], v[98:99] op_sel_hi:[1,0]
	v_pk_mul_f32 v[98:99], v[78:79], v[98:99] op_sel_hi:[1,0]
	v_cvt_pk_bf16_f32 v100, v100, v101
	v_pk_mul_f32 v[110:111], v[98:99], v[102:103]
	v_pk_mul_f32 v[102:103], v[106:107], v[102:103]
	v_pk_fma_f32 v[110:111], v[106:107], v[108:109], v[110:111] neg_lo:[0,0,1] neg_hi:[0,0,1]
	v_pk_fma_f32 v[98:99], v[98:99], v[108:109], v[102:103]
	v_cvt_pk_bf16_f32 v102, v114, v115
	v_cvt_pk_bf16_f32 v103, v110, v111
	v_cvt_pk_bf16_f32 v101, v98, v99
	global_store_dwordx2 v[104:105], v[102:103], off offset:48
	global_store_dwordx2 v[104:105], v[100:101], off offset:112

; DI u32x2 pk4(float a, float b, float c, float d) { u32x2 r; r.x = pk2(a, b); r.y = pk2(c, d); return r; }
;     ...
;             for (int mi = 0; mi < MI; ++mi) {
;                 const int tok = tok0 + wr * C::WROWS + mi * 32 + li, tl = tok - half * HALF_T;
;                 const f32x4 s0 = *(const f32x4*)(SSQ + tok * 12), s1 = *(const f32x4*)(SSQ + tok * 12 + 4);
;                 const float rs = __builtin_amdgcn_rsqf(((s0.x + s0.y) + (s0.z + s0.w) + (s1.x + s1.y) + (s1.z + s1.w)) * (1.f / 512.f) + EPS) * QSCALE;
;                 bf16_t* dst = Q + (size_t)tl * 3072 + head * 192 + part * 64;
;                 bf16_t* drow0 = Q + (size_t)(tok0 - half * HALF_T + wr * C::WROWS + mi * 32) * 3072 + head * 192 + part * 64;
;                 if (part < 2) {
;                     wave_rows_store(ebuf, l, drow0, 3072, [&](int ni, int g) { return pk4(acc[mi][ni][4 * g] * rs, acc[mi][ni][4 * g + 1] * rs, acc[mi][ni][4 * g + 2] * rs, acc[mi][ni][4 * g + 3] * rs); });
;                 } else {
; #pragma unroll
;                     for (int g = 0; g < 4; ++g) {
;                         const int i0 = 8 * g + 4 * h;
;                         const f32x4 c4 = *(const f32x4*)(COS + tok * 32 + i0), s4 = *(const f32x4*)(SIN + tok * 32 + i0);
;                         float o1[4], o2[4];
; #pragma unroll
;                         for (int c = 0; c < 4; ++c) { const float x1 = acc[mi][0][4 * g + c] * rs, x2 = acc[mi][1][4 * g + c] * rs; o1[c] = x1 * c4[c] - x2 * s4[c]; o2[c] = x1 * s4[c] + x2 * c4[c]; }
;                         *(u32x2*)(dst + i0) = pk4(o1[0], o1[1], o1[2], o1[3]);
;                         *(u32x2*)(dst + 32 + i0) = pk4(o2[0], o2[1], o2[2], o2[3]);
;                     }
.LBB0_828:
	s_or_b64 exec, exec, s[4:5]
	v_add_u32_e32 v64, 0x180, v96
	v_ashrrev_i32_e32 v65, 31, v64
	v_lshl_add_u64 v[70:71], v[64:65], 2, s[10:11]
	global_load_dwordx4 v[112:115], v[70:71], off offset:1536
	global_load_dwordx4 v[116:119], v[70:71], off offset:1552
	v_mov_b32_e32 v66, v120
	v_mov_b32_e32 v67, v121
	v_mov_b32_e32 v68, v122
	v_mov_b32_e32 v69, v123
	v_mov_b32_e32 v70, v124
	v_mov_b32_e32 v71, v125
	v_mov_b32_e32 v72, v126
	v_mov_b32_e32 v73, v127
	v_add_f32_e32 v65, v66, v67
	v_add_f32_e32 v66, v68, v69
	v_add_f32_e32 v67, v70, v71
	v_add_f32_e32 v65, v65, v66
	v_add_f32_e32 v65, v65, v67
	v_add_f32_e32 v66, v72, v73
	v_add_f32_e32 v65, v66, v65
	v_fmamk_f32 v65, v65, 0x3b000000, v252
	v_rsq_f32_e32 v65, v65
	s_nop 0
	v_mul_f32_e32 v66, 0x3dd53b94, v65
	s_and_saveexec_b64 s[4:5], s[38:39]
	s_xor_b64 s[4:5], exec, s[4:5]
	s_cbranch_execz .LBB0_830
	v_or_b32_e32 v65, 64, v139
	v_subrev_u32_e32 v67, s46, v65
	v_mad_i64_i32 v[80:81], s[18:19], v67, s7, v[128:129]
	v_lshlrev_b32_e32 v68, 5, v65
	v_ashrrev_i32_e32 v69, 31, v68
	v_readlane_b32 s18, v254, 34
	v_lshlrev_b64 v[68:69], 2, v[68:69]
	v_readlane_b32 s19, v254, 35
	v_mov_b32_e32 v131, v177
	v_pk_mul_f32 v[84:85], v[32:33], v[66:67] op_sel_hi:[1,0]
	v_lshl_add_u64 v[70:71], s[18:19], 0, v[68:69]
	v_readlane_b32 s18, v254, 36
	v_readlane_b32 s19, v254, 37
	v_pk_mul_f32 v[82:83], v[48:49], v[66:67] op_sel_hi:[1,0]
	v_mov_b32_e32 v133, v177
	v_lshl_add_u64 v[76:77], s[18:19], 0, v[68:69]
	v_lshl_add_u64 v[68:69], v[70:71], 0, v[130:131]
	v_lshl_add_u64 v[70:71], v[76:77], 0, v[130:131]
	global_load_dwordx4 v[72:75], v[68:69], off
	global_load_dwordx4 v[76:79], v[70:71], off
	s_waitcnt vmcnt(0)
	v_pk_mul_f32 v[86:87], v[84:85], v[76:77]
	s_nop 0
	v_pk_fma_f32 v[86:87], v[82:83], v[72:73], v[86:87] neg_lo:[0,0,1] neg_hi:[0,0,1]
	v_pk_mul_f32 v[76:77], v[82:83], v[76:77]
	v_pk_mul_f32 v[82:83], v[34:35], v[66:67] op_sel_hi:[1,0]
	v_pk_fma_f32 v[76:77], v[84:85], v[72:73], v[76:77]
	v_pk_mul_f32 v[72:73], v[50:51], v[66:67] op_sel_hi:[1,0]
	v_pk_mul_f32 v[84:85], v[82:83], v[78:79]
	v_cvt_pk_bf16_f32 v76, v76, v77
	v_pk_fma_f32 v[84:85], v[72:73], v[74:75], v[84:85] neg_lo:[0,0,1] neg_hi:[0,0,1]
	v_pk_mul_f32 v[72:73], v[72:73], v[78:79]
	v_cvt_pk_bf16_f32 v78, v86, v87
	v_pk_fma_f32 v[74:75], v[82:83], v[74:75], v[72:73]
	v_cvt_pk_bf16_f32 v79, v84, v85
	v_lshl_add_u64 v[72:73], v[80:81], 0, v[132:133]
	v_cvt_pk_bf16_f32 v77, v74, v75
	global_store_dwordx2 v[72:73], v[78:79], off
	global_store_dwordx2 v[72:73], v[76:77], off offset:64
	global_load_dwordx4 v[74:77], v[68:69], off offset:32
	s_nop 0
	global_load_dwordx4 v[78:81], v[70:71], off offset:32
	v_pk_mul_f32 v[84:85], v[36:37], v[66:67] op_sel_hi:[1,0]
	v_pk_mul_f32 v[82:83], v[52:53], v[66:67] op_sel_hi:[1,0]
	s_waitcnt vmcnt(0)
	v_pk_mul_f32 v[86:87], v[84:85], v[78:79]
	s_nop 0
	v_pk_fma_f32 v[86:87], v[82:83], v[74:75], v[86:87] neg_lo:[0,0,1] neg_hi:[0,0,1]
	v_pk_mul_f32 v[78:79], v[82:83], v[78:79]
	v_pk_mul_f32 v[82:83], v[38:39], v[66:67] op_sel_hi:[1,0]
	v_pk_fma_f32 v[74:75], v[84:85], v[74:75], v[78:79]
	v_pk_mul_f32 v[78:79], v[54:55], v[66:67] op_sel_hi:[1,0]
	v_pk_mul_f32 v[84:85], v[82:83], v[80:81]
	v_cvt_pk_bf16_f32 v74, v74, v75
	v_pk_fma_f32 v[84:85], v[78:79], v[76:77], v[84:85] neg_lo:[0,0,1] neg_hi:[0,0,1]
	v_pk_mul_f32 v[78:79], v[78:79], v[80:81]
	s_nop 0
	v_pk_fma_f32 v[76:77], v[82:83], v[76:77], v[78:79]
	v_cvt_pk_bf16_f32 v78, v86, v87
	v_cvt_pk_bf16_f32 v79, v84, v85
	v_cvt_pk_bf16_f32 v75, v76, v77
	global_store_dwordx2 v[72:73], v[78:79], off offset:16
	global_store_dwordx2 v[72:73], v[74:75], off offset:80
	global_load_dwordx4 v[74:77], v[68:69], off offset:64
	s_nop 0
	global_load_dwordx4 v[78:81], v[70:71], off offset:64
	v_pk_mul_f32 v[84:85], v[40:41], v[66:67] op_sel_hi:[1,0]
	v_pk_mul_f32 v[82:83], v[56:57], v[66:67] op_sel_hi:[1,0]
	s_waitcnt vmcnt(0)
	v_pk_mul_f32 v[86:87], v[84:85], v[78:79]
	s_nop 0
	v_pk_fma_f32 v[86:87], v[82:83], v[74:75], v[86:87] neg_lo:[0,0,1] neg_hi:[0,0,1]
	v_pk_mul_f32 v[78:79], v[82:83], v[78:79]
	v_pk_mul_f32 v[82:83], v[42:43], v[66:67] op_sel_hi:[1,0]
	v_pk_fma_f32 v[74:75], v[84:85], v[74:75], v[78:79]
	v_pk_mul_f32 v[78:79], v[58:59], v[66:67] op_sel_hi:[1,0]
	v_pk_mul_f32 v[84:85], v[82:83], v[80:81]
	v_cvt_pk_bf16_f32 v74, v74, v75
	v_pk_fma_f32 v[84:85], v[78:79], v[76:77], v[84:85] neg_lo:[0,0,1] neg_hi:[0,0,1]
	v_pk_mul_f32 v[78:79], v[78:79], v[80:81]
	v_pk_mul_f32 v[80:81], v[44:45], v[66:67] op_sel_hi:[1,0]
	v_pk_fma_f32 v[76:77], v[82:83], v[76:77], v[78:79]
	v_cvt_pk_bf16_f32 v78, v86, v87
	v_cvt_pk_bf16_f32 v79, v84, v85
	v_cvt_pk_bf16_f32 v75, v76, v77
	global_store_dwordx2 v[72:73], v[78:79], off offset:32
	global_store_dwordx2 v[72:73], v[74:75], off offset:96
	global_load_dwordx4 v[74:77], v[68:69], off offset:96
	s_nop 0
	global_load_dwordx4 v[68:71], v[70:71], off offset:96
	v_pk_mul_f32 v[78:79], v[60:61], v[66:67] op_sel_hi:[1,0]
	s_waitcnt vmcnt(0)
	v_pk_mul_f32 v[82:83], v[80:81], v[68:69]
	v_pk_mul_f32 v[68:69], v[78:79], v[68:69]
	v_pk_fma_f32 v[82:83], v[78:79], v[74:75], v[82:83] neg_lo:[0,0,1] neg_hi:[0,0,1]
	v_pk_fma_f32 v[68:69], v[80:81], v[74:75], v[68:69]
	v_pk_mul_f32 v[74:75], v[62:63], v[66:67] op_sel_hi:[1,0]
	v_pk_mul_f32 v[66:67], v[46:47], v[66:67] op_sel_hi:[1,0]
	v_cvt_pk_bf16_f32 v68, v68, v69
	v_pk_mul_f32 v[78:79], v[66:67], v[70:71]
	v_pk_mul_f32 v[70:71], v[74:75], v[70:71]
	v_pk_fma_f32 v[78:79], v[74:75], v[76:77], v[78:79] neg_lo:[0,0,1] neg_hi:[0,0,1]
	v_pk_fma_f32 v[66:67], v[66:67], v[76:77], v[70:71]
	v_cvt_pk_bf16_f32 v70, v82, v83
	v_cvt_pk_bf16_f32 v71, v78, v79
	v_cvt_pk_bf16_f32 v69, v66, v67
	global_store_dwordx2 v[72:73], v[70:71], off offset:48
	global_store_dwordx2 v[72:73], v[68:69], off offset:112

; DI u32x2 pk4(float a, float b, float c, float d) { u32x2 r; r.x = pk2(a, b); r.y = pk2(c, d); return r; }
;     ...
;             for (int mi = 0; mi < MI; ++mi) {
;                 const int tok = tok0 + wr * C::WROWS + mi * 32 + li, tl = tok - half * HALF_T;
;                 const f32x4 s0 = *(const f32x4*)(SSQ + tok * 12), s1 = *(const f32x4*)(SSQ + tok * 12 + 4);
;                 const float rs = __builtin_amdgcn_rsqf(((s0.x + s0.y) + (s0.z + s0.w) + (s1.x + s1.y) + (s1.z + s1.w)) * (1.f / 512.f) + EPS) * QSCALE;
;                 bf16_t* dst = Q + (size_t)tl * 3072 + head * 192 + part * 64;
;                 bf16_t* drow0 = Q + (size_t)(tok0 - half * HALF_T + wr * C::WROWS + mi * 32) * 3072 + head * 192 + part * 64;
;                 if (part < 2) {
;                     wave_rows_store(ebuf, l, drow0, 3072, [&](int ni, int g) { return pk4(acc[mi][ni][4 * g] * rs, acc[mi][ni][4 * g + 1] * rs, acc[mi][ni][4 * g + 2] * rs, acc[mi][ni][4 * g + 3] * rs); });
;                 } else {
; #pragma unroll
;                     for (int g = 0; g < 4; ++g) {
;                         const int i0 = 8 * g + 4 * h;
;                         const f32x4 c4 = *(const f32x4*)(COS + tok * 32 + i0), s4 = *(const f32x4*)(SIN + tok * 32 + i0);
;                         float o1[4], o2[4];
; #pragma unroll
;                         for (int c = 0; c < 4; ++c) { const float x1 = acc[mi][0][4 * g + c] * rs, x2 = acc[mi][1][4 * g + c] * rs; o1[c] = x1 * c4[c] - x2 * s4[c]; o2[c] = x1 * s4[c] + x2 * c4[c]; }
;                         *(u32x2*)(dst + i0) = pk4(o1[0], o1[1], o1[2], o1[3]);
;                         *(u32x2*)(dst + 32 + i0) = pk4(o2[0], o2[1], o2[2], o2[3]);
;                     }
.LBB0_832:
	s_or_b64 exec, exec, s[4:5]
	v_add_u32_e32 v32, 0x180, v64
	v_ashrrev_i32_e32 v33, 31, v32
	v_lshl_add_u64 v[36:37], v[32:33], 2, s[10:11]
	s_waitcnt vmcnt(4)
	v_mov_b32_e32 v32, v112
	v_mov_b32_e32 v33, v113
	v_mov_b32_e32 v34, v114
	v_mov_b32_e32 v35, v115
	v_mov_b32_e32 v36, v116
	v_mov_b32_e32 v37, v117
	v_mov_b32_e32 v38, v118
	v_mov_b32_e32 v39, v119
	v_add_f32_e32 v32, v32, v33
	v_add_f32_e32 v33, v34, v35
	v_add_f32_e32 v34, v36, v37
	v_add_f32_e32 v32, v32, v33
	v_add_f32_e32 v32, v32, v34
	v_add_f32_e32 v33, v38, v39
	v_add_f32_e32 v32, v33, v32
	v_fmamk_f32 v32, v32, 0x3b000000, v252
	v_rsq_f32_e32 v32, v32
	s_nop 0
	v_mul_f32_e32 v32, 0x3dd53b94, v32
	s_and_saveexec_b64 s[4:5], s[38:39]
	s_xor_b64 s[4:5], exec, s[4:5]
	s_cbranch_execz .LBB0_834
	v_or_b32_e32 v33, 0x60, v139
	v_subrev_u32_e32 v34, s46, v33
	v_mad_i64_i32 v[46:47], s[18:19], v34, s7, v[128:129]
	v_lshlrev_b32_e32 v34, 5, v33
	v_ashrrev_i32_e32 v35, 31, v34
	v_readlane_b32 s18, v254, 34
	v_lshlrev_b64 v[34:35], 2, v[34:35]
	v_readlane_b32 s19, v254, 35
	v_mov_b32_e32 v131, v177
	v_pk_mul_f32 v[50:51], v[0:1], v[32:33] op_sel_hi:[1,0]
	v_lshl_add_u64 v[36:37], s[18:19], 0, v[34:35]
	v_readlane_b32 s18, v254, 36
	v_readlane_b32 s19, v254, 37
	v_pk_mul_f32 v[48:49], v[16:17], v[32:33] op_sel_hi:[1,0]
	v_mov_b32_e32 v133, v177
	v_lshl_add_u64 v[42:43], s[18:19], 0, v[34:35]
	v_lshl_add_u64 v[34:35], v[36:37], 0, v[130:131]
	v_lshl_add_u64 v[36:37], v[42:43], 0, v[130:131]
	global_load_dwordx4 v[38:41], v[34:35], off
	global_load_dwordx4 v[42:45], v[36:37], off
	s_waitcnt vmcnt(0)
	v_pk_mul_f32 v[52:53], v[50:51], v[42:43]
	s_nop 0
	v_pk_fma_f32 v[52:53], v[48:49], v[38:39], v[52:53] neg_lo:[0,0,1] neg_hi:[0,0,1]
	v_pk_mul_f32 v[42:43], v[48:49], v[42:43]
	v_pk_mul_f32 v[48:49], v[2:3], v[32:33] op_sel_hi:[1,0]
	v_pk_fma_f32 v[42:43], v[50:51], v[38:39], v[42:43]
	v_pk_mul_f32 v[38:39], v[18:19], v[32:33] op_sel_hi:[1,0]
	v_pk_mul_f32 v[50:51], v[48:49], v[44:45]
	v_cvt_pk_bf16_f32 v42, v42, v43
	v_pk_fma_f32 v[50:51], v[38:39], v[40:41], v[50:51] neg_lo:[0,0,1] neg_hi:[0,0,1]
	v_pk_mul_f32 v[38:39], v[38:39], v[44:45]
	v_cvt_pk_bf16_f32 v44, v52, v53
	v_pk_fma_f32 v[40:41], v[48:49], v[40:41], v[38:39]
	v_cvt_pk_bf16_f32 v45, v50, v51
	v_lshl_add_u64 v[38:39], v[46:47], 0, v[132:133]
	v_cvt_pk_bf16_f32 v43, v40, v41
	global_store_dwordx2 v[38:39], v[44:45], off
	global_store_dwordx2 v[38:39], v[42:43], off offset:64
	global_load_dwordx4 v[40:43], v[34:35], off offset:32
	s_nop 0
	global_load_dwordx4 v[44:47], v[36:37], off offset:32
	v_pk_mul_f32 v[50:51], v[4:5], v[32:33] op_sel_hi:[1,0]
	v_pk_mul_f32 v[48:49], v[20:21], v[32:33] op_sel_hi:[1,0]
	s_waitcnt vmcnt(0)
	v_pk_mul_f32 v[52:53], v[50:51], v[44:45]
	s_nop 0
	v_pk_fma_f32 v[52:53], v[48:49], v[40:41], v[52:53] neg_lo:[0,0,1] neg_hi:[0,0,1]
	v_pk_mul_f32 v[44:45], v[48:49], v[44:45]
	v_pk_mul_f32 v[48:49], v[6:7], v[32:33] op_sel_hi:[1,0]
	v_pk_fma_f32 v[40:41], v[50:51], v[40:41], v[44:45]
	v_pk_mul_f32 v[44:45], v[22:23], v[32:33] op_sel_hi:[1,0]
	v_pk_mul_f32 v[50:51], v[48:49], v[46:47]
	v_cvt_pk_bf16_f32 v40, v40, v41
	v_pk_fma_f32 v[50:51], v[44:45], v[42:43], v[50:51] neg_lo:[0,0,1] neg_hi:[0,0,1]
	v_pk_mul_f32 v[44:45], v[44:45], v[46:47]
	s_nop 0
	v_pk_fma_f32 v[42:43], v[48:49], v[42:43], v[44:45]
	v_cvt_pk_bf16_f32 v44, v52, v53
	v_cvt_pk_bf16_f32 v45, v50, v51
	v_cvt_pk_bf16_f32 v41, v42, v43
	global_store_dwordx2 v[38:39], v[44:45], off offset:16
	global_store_dwordx2 v[38:39], v[40:41], off offset:80
	global_load_dwordx4 v[40:43], v[34:35], off offset:64
	s_nop 0
	global_load_dwordx4 v[44:47], v[36:37], off offset:64
	v_pk_mul_f32 v[50:51], v[8:9], v[32:33] op_sel_hi:[1,0]
	v_pk_mul_f32 v[48:49], v[24:25], v[32:33] op_sel_hi:[1,0]
	s_waitcnt vmcnt(0)
	v_pk_mul_f32 v[52:53], v[50:51], v[44:45]
	s_nop 0
	v_pk_fma_f32 v[52:53], v[48:49], v[40:41], v[52:53] neg_lo:[0,0,1] neg_hi:[0,0,1]
	v_pk_mul_f32 v[44:45], v[48:49], v[44:45]
	v_pk_mul_f32 v[48:49], v[10:11], v[32:33] op_sel_hi:[1,0]
	v_pk_fma_f32 v[40:41], v[50:51], v[40:41], v[44:45]
	v_pk_mul_f32 v[44:45], v[26:27], v[32:33] op_sel_hi:[1,0]
	v_pk_mul_f32 v[50:51], v[48:49], v[46:47]
	v_cvt_pk_bf16_f32 v40, v40, v41
	v_pk_fma_f32 v[50:51], v[44:45], v[42:43], v[50:51] neg_lo:[0,0,1] neg_hi:[0,0,1]
	v_pk_mul_f32 v[44:45], v[44:45], v[46:47]
	v_pk_mul_f32 v[46:47], v[12:13], v[32:33] op_sel_hi:[1,0]
	v_pk_fma_f32 v[42:43], v[48:49], v[42:43], v[44:45]
	v_cvt_pk_bf16_f32 v44, v52, v53
	v_cvt_pk_bf16_f32 v45, v50, v51
	v_cvt_pk_bf16_f32 v41, v42, v43
	global_store_dwordx2 v[38:39], v[44:45], off offset:32
	global_store_dwordx2 v[38:39], v[40:41], off offset:96
	global_load_dwordx4 v[40:43], v[34:35], off offset:96
	s_nop 0
	global_load_dwordx4 v[34:37], v[36:37], off offset:96
	v_pk_mul_f32 v[44:45], v[28:29], v[32:33] op_sel_hi:[1,0]
	s_waitcnt vmcnt(0)
	v_pk_mul_f32 v[48:49], v[46:47], v[34:35]
	v_pk_mul_f32 v[34:35], v[44:45], v[34:35]
	v_pk_fma_f32 v[48:49], v[44:45], v[40:41], v[48:49] neg_lo:[0,0,1] neg_hi:[0,0,1]
	v_pk_fma_f32 v[34:35], v[46:47], v[40:41], v[34:35]
	v_pk_mul_f32 v[40:41], v[30:31], v[32:33] op_sel_hi:[1,0]
	v_pk_mul_f32 v[32:33], v[14:15], v[32:33] op_sel_hi:[1,0]
	v_cvt_pk_bf16_f32 v34, v34, v35
	v_pk_mul_f32 v[44:45], v[32:33], v[36:37]
	v_pk_mul_f32 v[36:37], v[40:41], v[36:37]
	v_pk_fma_f32 v[44:45], v[40:41], v[42:43], v[44:45] neg_lo:[0,0,1] neg_hi:[0,0,1]
	v_pk_fma_f32 v[32:33], v[32:33], v[42:43], v[36:37]
	v_cvt_pk_bf16_f32 v36, v48, v49
	v_cvt_pk_bf16_f32 v37, v44, v45
	v_cvt_pk_bf16_f32 v35, v32, v33
	global_store_dwordx2 v[38:39], v[36:37], off offset:48
	global_store_dwordx2 v[38:39], v[34:35], off offset:112
